# fold_tile (W_ob branch) staging loads issued up front instead of two at a time
# speedup vs baseline: 1.0233x; 1.0108x over previous
.LBB0_144:
	s_cmpk_gt_i32 s6, 0x1ff
	s_mov_b64 s[2:3], -1
	s_cbranch_scc0 .LBB0_148
	s_add_i32 s2, s6, 0xfffffe00
	s_lshr_b32 s2, s2, 6
	s_lshl_b32 s3, s6, 4
	s_lshl_b32 s56, s2, 7
	s_and_b32 s15, s3, 0x3c0
	s_lshl_b64 s[16:17], s[56:57], 12
	s_add_u32 s3, s11, s16
	v_mov_b32_e32 v2, v192
	s_addc_u32 s17, s12, s17
	s_lshl_b32 s16, s15, 2
	s_add_u32 s16, s3, s16
	s_waitcnt vmcnt(1)
	v_and_b32_e32 v26, 63, v2
	v_add_u32_e32 v18, 0x100, v2
	v_ashrrev_i32_e32 v6, 6, v2
	s_addc_u32 s17, s17, 0
	v_lshlrev_b32_e32 v176, 2, v26
	v_ashrrev_i32_e32 v4, 6, v18
	v_ashrrev_i32_e32 v7, 31, v6
	v_lshl_add_u64 v[0:1], s[16:17], 0, v[176:177]
	v_ashrrev_i32_e32 v5, 31, v4
	v_lshlrev_b64 v[10:11], 12, v[6:7]
	v_lshlrev_b64 v[8:9], 12, v[4:5]
	v_lshl_add_u64 v[10:11], v[0:1], 0, v[10:11]
	s_barrier
	v_and_b32_e32 v3, 63, v2
	v_lshrrev_b32_e32 v4, 6, v2
	v_lshlrev_b32_e32 v5, 2, v3
	v_lshl_add_u32 v5, v4, 12, v5
	v_mul_u32_u24_e32 v6, 0x204, v3
	v_lshl_add_u32 v6, v4, 2, v6
	global_load_dword v64, v5, s[16:17]
	v_add_u32_e32 v5, 0x4000, v5
	global_load_dword v65, v5, s[16:17]
	v_add_u32_e32 v5, 0x4000, v5
	global_load_dword v66, v5, s[16:17]
	v_add_u32_e32 v5, 0x4000, v5
	global_load_dword v67, v5, s[16:17]
	v_add_u32_e32 v5, 0x4000, v5
	global_load_dword v68, v5, s[16:17]
	v_add_u32_e32 v5, 0x4000, v5
	global_load_dword v69, v5, s[16:17]
	v_add_u32_e32 v5, 0x4000, v5
	global_load_dword v70, v5, s[16:17]
	v_add_u32_e32 v5, 0x4000, v5
	global_load_dword v71, v5, s[16:17]
	v_add_u32_e32 v5, 0x4000, v5
	global_load_dword v72, v5, s[16:17]
	v_add_u32_e32 v5, 0x4000, v5
	global_load_dword v73, v5, s[16:17]
	v_add_u32_e32 v5, 0x4000, v5
	global_load_dword v74, v5, s[16:17]
	v_add_u32_e32 v5, 0x4000, v5
	global_load_dword v75, v5, s[16:17]
	v_add_u32_e32 v5, 0x4000, v5
	global_load_dword v76, v5, s[16:17]
	v_add_u32_e32 v5, 0x4000, v5
	global_load_dword v77, v5, s[16:17]
	v_add_u32_e32 v5, 0x4000, v5
	global_load_dword v78, v5, s[16:17]
	v_add_u32_e32 v5, 0x4000, v5
	global_load_dword v79, v5, s[16:17]
	v_add_u32_e32 v5, 0x4000, v5
	global_load_dword v80, v5, s[16:17]
	v_add_u32_e32 v5, 0x4000, v5
	global_load_dword v81, v5, s[16:17]
	v_add_u32_e32 v5, 0x4000, v5
	global_load_dword v82, v5, s[16:17]
	v_add_u32_e32 v5, 0x4000, v5
	global_load_dword v83, v5, s[16:17]
	v_add_u32_e32 v5, 0x4000, v5
	global_load_dword v84, v5, s[16:17]
	v_add_u32_e32 v5, 0x4000, v5
	global_load_dword v85, v5, s[16:17]
	v_add_u32_e32 v5, 0x4000, v5
	global_load_dword v86, v5, s[16:17]
	v_add_u32_e32 v5, 0x4000, v5
	global_load_dword v87, v5, s[16:17]
	v_add_u32_e32 v5, 0x4000, v5
	global_load_dword v88, v5, s[16:17]
	v_add_u32_e32 v5, 0x4000, v5
	global_load_dword v89, v5, s[16:17]
	v_add_u32_e32 v5, 0x4000, v5
	global_load_dword v90, v5, s[16:17]
	v_add_u32_e32 v5, 0x4000, v5
	global_load_dword v91, v5, s[16:17]
	v_add_u32_e32 v5, 0x4000, v5
	global_load_dword v92, v5, s[16:17]
	v_add_u32_e32 v5, 0x4000, v5
	global_load_dword v93, v5, s[16:17]
	v_add_u32_e32 v5, 0x4000, v5
	global_load_dword v94, v5, s[16:17]
	v_add_u32_e32 v5, 0x4000, v5
	global_load_dword v95, v5, s[16:17]
	s_movk_i32 s20, 0x204
	s_lshl_b32 s3, s6, 6
	s_and_b32 s16, s3, 0xc0
	s_mov_b32 s3, s57
	s_lshl_b64 s[18:19], s[2:3], 17
	s_add_u32 s3, s9, s18
	s_addc_u32 s17, s10, s19
	s_lshl_b32 s18, s16, 9
	s_add_u32 s18, s3, s18
	s_addc_u32 s19, s17, 0
	s_mov_b32 s3, 0
	v_lshlrev_b32_e32 v7, 2, v2
	v_lshrrev_b32_e32 v8, 7, v2
	v_and_b32_e32 v9, 0x7f, v2
	v_mul_u32_u24_e32 v8, 0x204, v8
	v_lshl_add_u32 v8, v9, 2, v8
	global_load_dword v96, v7, s[18:19]
	global_load_dword v97, v7, s[18:19] offset:1024
	global_load_dword v98, v7, s[18:19] offset:2048
	global_load_dword v99, v7, s[18:19] offset:3072
	v_add_u32_e32 v7, 0x1000, v7
	global_load_dword v100, v7, s[18:19]
	global_load_dword v101, v7, s[18:19] offset:1024
	global_load_dword v102, v7, s[18:19] offset:2048
	global_load_dword v103, v7, s[18:19] offset:3072
	v_add_u32_e32 v7, 0x1000, v7
	global_load_dword v104, v7, s[18:19]
	global_load_dword v105, v7, s[18:19] offset:1024
	global_load_dword v106, v7, s[18:19] offset:2048
	global_load_dword v107, v7, s[18:19] offset:3072
	v_add_u32_e32 v7, 0x1000, v7
	global_load_dword v108, v7, s[18:19]
	global_load_dword v109, v7, s[18:19] offset:1024
	global_load_dword v110, v7, s[18:19] offset:2048
	global_load_dword v111, v7, s[18:19] offset:3072
	v_add_u32_e32 v7, 0x1000, v7
	global_load_dword v112, v7, s[18:19]
	global_load_dword v113, v7, s[18:19] offset:1024
	global_load_dword v114, v7, s[18:19] offset:2048
	global_load_dword v115, v7, s[18:19] offset:3072
	v_add_u32_e32 v7, 0x1000, v7
	global_load_dword v116, v7, s[18:19]
	global_load_dword v117, v7, s[18:19] offset:1024
	global_load_dword v118, v7, s[18:19] offset:2048
	global_load_dword v119, v7, s[18:19] offset:3072
	v_add_u32_e32 v7, 0x1000, v7
	global_load_dword v120, v7, s[18:19]
	global_load_dword v121, v7, s[18:19] offset:1024
	global_load_dword v122, v7, s[18:19] offset:2048
	global_load_dword v123, v7, s[18:19] offset:3072
	v_add_u32_e32 v7, 0x1000, v7
	global_load_dword v124, v7, s[18:19]
	global_load_dword v125, v7, s[18:19] offset:1024
	global_load_dword v126, v7, s[18:19] offset:2048
	global_load_dword v127, v7, s[18:19] offset:3072
	s_waitcnt vmcnt(32)
	ds_write_b32 v6, v64
	ds_write_b32 v6, v65 offset:16
	ds_write_b32 v6, v66 offset:32
	ds_write_b32 v6, v67 offset:48
	ds_write_b32 v6, v68 offset:64
	ds_write_b32 v6, v69 offset:80
	ds_write_b32 v6, v70 offset:96
	ds_write_b32 v6, v71 offset:112
	ds_write_b32 v6, v72 offset:128
	ds_write_b32 v6, v73 offset:144
	ds_write_b32 v6, v74 offset:160
	ds_write_b32 v6, v75 offset:176
	ds_write_b32 v6, v76 offset:192
	ds_write_b32 v6, v77 offset:208
	ds_write_b32 v6, v78 offset:224
	ds_write_b32 v6, v79 offset:240
	ds_write_b32 v6, v80 offset:256
	ds_write_b32 v6, v81 offset:272
	ds_write_b32 v6, v82 offset:288
	ds_write_b32 v6, v83 offset:304
	ds_write_b32 v6, v84 offset:320
	ds_write_b32 v6, v85 offset:336
	ds_write_b32 v6, v86 offset:352
	ds_write_b32 v6, v87 offset:368
	ds_write_b32 v6, v88 offset:384
	ds_write_b32 v6, v89 offset:400
	ds_write_b32 v6, v90 offset:416
	ds_write_b32 v6, v91 offset:432
	ds_write_b32 v6, v92 offset:448
	ds_write_b32 v6, v93 offset:464
	ds_write_b32 v6, v94 offset:480
	ds_write_b32 v6, v95 offset:496
	s_waitcnt vmcnt(0)
	ds_write_b32 v8, v96 offset:33024
	ds_write_b32 v8, v97 offset:34056
	ds_write_b32 v8, v98 offset:35088
	ds_write_b32 v8, v99 offset:36120
	ds_write_b32 v8, v100 offset:37152
	ds_write_b32 v8, v101 offset:38184
	ds_write_b32 v8, v102 offset:39216
	ds_write_b32 v8, v103 offset:40248
	ds_write_b32 v8, v104 offset:41280
	ds_write_b32 v8, v105 offset:42312
	ds_write_b32 v8, v106 offset:43344
	ds_write_b32 v8, v107 offset:44376
	ds_write_b32 v8, v108 offset:45408
	ds_write_b32 v8, v109 offset:46440
	ds_write_b32 v8, v110 offset:47472
	ds_write_b32 v8, v111 offset:48504
	ds_write_b32 v8, v112 offset:49536
	ds_write_b32 v8, v113 offset:50568
	ds_write_b32 v8, v114 offset:51600
	ds_write_b32 v8, v115 offset:52632
	ds_write_b32 v8, v116 offset:53664
	ds_write_b32 v8, v117 offset:54696
	ds_write_b32 v8, v118 offset:55728
	ds_write_b32 v8, v119 offset:56760
	ds_write_b32 v8, v120 offset:57792
	ds_write_b32 v8, v121 offset:58824
	ds_write_b32 v8, v122 offset:59856
	ds_write_b32 v8, v123 offset:60888
	ds_write_b32 v8, v124 offset:61920
	ds_write_b32 v8, v125 offset:62952
	ds_write_b32 v8, v126 offset:63984
	ds_write_b32 v8, v127 offset:65016
	v_ashrrev_i32_e32 v0, 2, v2
	v_and_b32_e32 v1, 15, v2
	v_and_b32_e32 v12, -4, v0
	v_or_b32_e32 v0, 3, v0
	v_mov_b32_e32 v2, 0
	v_mul_lo_u32 v13, v12, s20
	v_mul_lo_u32 v20, v0, s20
	v_mad_u32_u24 v21, v1, s20, v210
	v_mov_b32_e32 v3, v2
	v_mov_b32_e32 v4, v2
	v_mov_b32_e32 v5, v2
	v_mov_b32_e32 v6, v2
	v_mov_b32_e32 v7, v2
	v_mov_b32_e32 v8, v2
	v_mov_b32_e32 v9, v2
	v_mov_b32_e32 v10, v2
	v_mov_b32_e32 v11, v2
	v_mov_b32_e32 v14, v2
	v_mov_b32_e32 v15, v2
	v_mov_b32_e32 v16, v2
	v_mov_b32_e32 v17, v2
	v_mov_b32_e32 v18, v2
	v_mov_b32_e32 v19, v2
	s_waitcnt lgkmcnt(0)
	s_barrier

.LBB0_1518:
	s_cmpk_gt_i32 s12, 0x1ff
	s_mov_b64 s[10:11], -1
	s_cbranch_scc0 .LBB0_1522
	s_add_i32 s10, s12, 0xfffffe00
	s_lshr_b32 s10, s10, 6
	s_lshl_b32 s11, s12, 4
	s_lshl_b32 s56, s10, 7
	s_and_b32 s15, s11, 0x3c0
	s_lshl_b64 s[16:17], s[56:57], 12
	s_waitcnt lgkmcnt(0)
	s_add_u32 s11, s2, s16
	v_mov_b32_e32 v2, v192
	s_addc_u32 s17, s3, s17
	s_lshl_b32 s16, s15, 2
	s_add_u32 s16, s11, s16
	s_waitcnt vmcnt(1)
	v_and_b32_e32 v26, 63, v2
	v_add_u32_e32 v18, 0x100, v2
	v_ashrrev_i32_e32 v6, 6, v2
	s_addc_u32 s17, s17, 0
	v_lshlrev_b32_e32 v176, 2, v26
	v_ashrrev_i32_e32 v4, 6, v18
	v_ashrrev_i32_e32 v7, 31, v6
	v_lshl_add_u64 v[0:1], s[16:17], 0, v[176:177]
	v_ashrrev_i32_e32 v5, 31, v4
	v_lshlrev_b64 v[10:11], 12, v[6:7]
	v_lshlrev_b64 v[8:9], 12, v[4:5]
	v_lshl_add_u64 v[10:11], v[0:1], 0, v[10:11]
	s_barrier
	v_and_b32_e32 v3, 63, v2
	v_lshrrev_b32_e32 v4, 6, v2
	v_lshlrev_b32_e32 v5, 2, v3
	v_lshl_add_u32 v5, v4, 12, v5
	v_mul_u32_u24_e32 v6, 0x204, v3
	v_lshl_add_u32 v6, v4, 2, v6
	global_load_dword v64, v5, s[16:17]
	v_add_u32_e32 v5, 0x4000, v5
	global_load_dword v65, v5, s[16:17]
	v_add_u32_e32 v5, 0x4000, v5
	global_load_dword v66, v5, s[16:17]
	v_add_u32_e32 v5, 0x4000, v5
	global_load_dword v67, v5, s[16:17]
	v_add_u32_e32 v5, 0x4000, v5
	global_load_dword v68, v5, s[16:17]
	v_add_u32_e32 v5, 0x4000, v5
	global_load_dword v69, v5, s[16:17]
	v_add_u32_e32 v5, 0x4000, v5
	global_load_dword v70, v5, s[16:17]
	v_add_u32_e32 v5, 0x4000, v5
	global_load_dword v71, v5, s[16:17]
	v_add_u32_e32 v5, 0x4000, v5
	global_load_dword v72, v5, s[16:17]
	v_add_u32_e32 v5, 0x4000, v5
	global_load_dword v73, v5, s[16:17]
	v_add_u32_e32 v5, 0x4000, v5
	global_load_dword v74, v5, s[16:17]
	v_add_u32_e32 v5, 0x4000, v5
	global_load_dword v75, v5, s[16:17]
	v_add_u32_e32 v5, 0x4000, v5
	global_load_dword v76, v5, s[16:17]
	v_add_u32_e32 v5, 0x4000, v5
	global_load_dword v77, v5, s[16:17]
	v_add_u32_e32 v5, 0x4000, v5
	global_load_dword v78, v5, s[16:17]
	v_add_u32_e32 v5, 0x4000, v5
	global_load_dword v79, v5, s[16:17]
	v_add_u32_e32 v5, 0x4000, v5
	global_load_dword v80, v5, s[16:17]
	v_add_u32_e32 v5, 0x4000, v5
	global_load_dword v81, v5, s[16:17]
	v_add_u32_e32 v5, 0x4000, v5
	global_load_dword v82, v5, s[16:17]
	v_add_u32_e32 v5, 0x4000, v5
	global_load_dword v83, v5, s[16:17]
	v_add_u32_e32 v5, 0x4000, v5
	global_load_dword v84, v5, s[16:17]
	v_add_u32_e32 v5, 0x4000, v5
	global_load_dword v85, v5, s[16:17]
	v_add_u32_e32 v5, 0x4000, v5
	global_load_dword v86, v5, s[16:17]
	v_add_u32_e32 v5, 0x4000, v5
	global_load_dword v87, v5, s[16:17]
	v_add_u32_e32 v5, 0x4000, v5
	global_load_dword v88, v5, s[16:17]
	v_add_u32_e32 v5, 0x4000, v5
	global_load_dword v89, v5, s[16:17]
	v_add_u32_e32 v5, 0x4000, v5
	global_load_dword v90, v5, s[16:17]
	v_add_u32_e32 v5, 0x4000, v5
	global_load_dword v91, v5, s[16:17]
	v_add_u32_e32 v5, 0x4000, v5
	global_load_dword v92, v5, s[16:17]
	v_add_u32_e32 v5, 0x4000, v5
	global_load_dword v93, v5, s[16:17]
	v_add_u32_e32 v5, 0x4000, v5
	global_load_dword v94, v5, s[16:17]
	v_add_u32_e32 v5, 0x4000, v5
	global_load_dword v95, v5, s[16:17]
	s_movk_i32 s20, 0x204
	s_lshl_b32 s11, s12, 6
	s_and_b32 s16, s11, 0xc0
	s_mov_b32 s11, s57
	s_lshl_b64 s[18:19], s[10:11], 17
	s_add_u32 s11, s6, s18
	s_addc_u32 s17, s7, s19
	s_lshl_b32 s18, s16, 9
	s_add_u32 s18, s11, s18
	s_addc_u32 s19, s17, 0
	s_mov_b32 s11, 0
	v_lshlrev_b32_e32 v7, 2, v2
	v_lshrrev_b32_e32 v8, 7, v2
	v_and_b32_e32 v9, 0x7f, v2
	v_mul_u32_u24_e32 v8, 0x204, v8
	v_lshl_add_u32 v8, v9, 2, v8
	global_load_dword v96, v7, s[18:19]
	global_load_dword v97, v7, s[18:19] offset:1024
	global_load_dword v98, v7, s[18:19] offset:2048
	global_load_dword v99, v7, s[18:19] offset:3072
	v_add_u32_e32 v7, 0x1000, v7
	global_load_dword v100, v7, s[18:19]
	global_load_dword v101, v7, s[18:19] offset:1024
	global_load_dword v102, v7, s[18:19] offset:2048
	global_load_dword v103, v7, s[18:19] offset:3072
	v_add_u32_e32 v7, 0x1000, v7
	global_load_dword v104, v7, s[18:19]
	global_load_dword v105, v7, s[18:19] offset:1024
	global_load_dword v106, v7, s[18:19] offset:2048
	global_load_dword v107, v7, s[18:19] offset:3072
	v_add_u32_e32 v7, 0x1000, v7
	global_load_dword v108, v7, s[18:19]
	global_load_dword v109, v7, s[18:19] offset:1024
	global_load_dword v110, v7, s[18:19] offset:2048
	global_load_dword v111, v7, s[18:19] offset:3072
	v_add_u32_e32 v7, 0x1000, v7
	global_load_dword v112, v7, s[18:19]
	global_load_dword v113, v7, s[18:19] offset:1024
	global_load_dword v114, v7, s[18:19] offset:2048
	global_load_dword v115, v7, s[18:19] offset:3072
	v_add_u32_e32 v7, 0x1000, v7
	global_load_dword v116, v7, s[18:19]
	global_load_dword v117, v7, s[18:19] offset:1024
	global_load_dword v118, v7, s[18:19] offset:2048
	global_load_dword v119, v7, s[18:19] offset:3072
	v_add_u32_e32 v7, 0x1000, v7
	global_load_dword v120, v7, s[18:19]
	global_load_dword v121, v7, s[18:19] offset:1024
	global_load_dword v122, v7, s[18:19] offset:2048
	global_load_dword v123, v7, s[18:19] offset:3072
	v_add_u32_e32 v7, 0x1000, v7
	global_load_dword v124, v7, s[18:19]
	global_load_dword v125, v7, s[18:19] offset:1024
	global_load_dword v126, v7, s[18:19] offset:2048
	global_load_dword v127, v7, s[18:19] offset:3072
	s_waitcnt vmcnt(32)
	ds_write_b32 v6, v64
	ds_write_b32 v6, v65 offset:16
	ds_write_b32 v6, v66 offset:32
	ds_write_b32 v6, v67 offset:48
	ds_write_b32 v6, v68 offset:64
	ds_write_b32 v6, v69 offset:80
	ds_write_b32 v6, v70 offset:96
	ds_write_b32 v6, v71 offset:112
	ds_write_b32 v6, v72 offset:128
	ds_write_b32 v6, v73 offset:144
	ds_write_b32 v6, v74 offset:160
	ds_write_b32 v6, v75 offset:176
	ds_write_b32 v6, v76 offset:192
	ds_write_b32 v6, v77 offset:208
	ds_write_b32 v6, v78 offset:224
	ds_write_b32 v6, v79 offset:240
	ds_write_b32 v6, v80 offset:256
	ds_write_b32 v6, v81 offset:272
	ds_write_b32 v6, v82 offset:288
	ds_write_b32 v6, v83 offset:304
	ds_write_b32 v6, v84 offset:320
	ds_write_b32 v6, v85 offset:336
	ds_write_b32 v6, v86 offset:352
	ds_write_b32 v6, v87 offset:368
	ds_write_b32 v6, v88 offset:384
	ds_write_b32 v6, v89 offset:400
	ds_write_b32 v6, v90 offset:416
	ds_write_b32 v6, v91 offset:432
	ds_write_b32 v6, v92 offset:448
	ds_write_b32 v6, v93 offset:464
	ds_write_b32 v6, v94 offset:480
	ds_write_b32 v6, v95 offset:496
	s_waitcnt vmcnt(0)
	ds_write_b32 v8, v96 offset:33024
	ds_write_b32 v8, v97 offset:34056
	ds_write_b32 v8, v98 offset:35088
	ds_write_b32 v8, v99 offset:36120
	ds_write_b32 v8, v100 offset:37152
	ds_write_b32 v8, v101 offset:38184
	ds_write_b32 v8, v102 offset:39216
	ds_write_b32 v8, v103 offset:40248
	ds_write_b32 v8, v104 offset:41280
	ds_write_b32 v8, v105 offset:42312
	ds_write_b32 v8, v106 offset:43344
	ds_write_b32 v8, v107 offset:44376
	ds_write_b32 v8, v108 offset:45408
	ds_write_b32 v8, v109 offset:46440
	ds_write_b32 v8, v110 offset:47472
	ds_write_b32 v8, v111 offset:48504
	ds_write_b32 v8, v112 offset:49536
	ds_write_b32 v8, v113 offset:50568
	ds_write_b32 v8, v114 offset:51600
	ds_write_b32 v8, v115 offset:52632
	ds_write_b32 v8, v116 offset:53664
	ds_write_b32 v8, v117 offset:54696
	ds_write_b32 v8, v118 offset:55728
	ds_write_b32 v8, v119 offset:56760
	ds_write_b32 v8, v120 offset:57792
	ds_write_b32 v8, v121 offset:58824
	ds_write_b32 v8, v122 offset:59856
	ds_write_b32 v8, v123 offset:60888
	ds_write_b32 v8, v124 offset:61920
	ds_write_b32 v8, v125 offset:62952
	ds_write_b32 v8, v126 offset:63984
	ds_write_b32 v8, v127 offset:65016
	v_ashrrev_i32_e32 v0, 2, v2
	v_and_b32_e32 v1, 15, v2
	v_and_b32_e32 v12, -4, v0
	v_or_b32_e32 v0, 3, v0
	v_mov_b32_e32 v2, 0
	v_mul_lo_u32 v13, v12, s20
	v_mul_lo_u32 v20, v0, s20
	v_mad_u32_u24 v21, v1, s20, v210
	v_mov_b32_e32 v3, v2
	v_mov_b32_e32 v4, v2
	v_mov_b32_e32 v5, v2
	v_mov_b32_e32 v6, v2
	v_mov_b32_e32 v7, v2
	v_mov_b32_e32 v8, v2
	v_mov_b32_e32 v9, v2
	v_mov_b32_e32 v10, v2
	v_mov_b32_e32 v11, v2
	v_mov_b32_e32 v14, v2
	v_mov_b32_e32 v15, v2
	v_mov_b32_e32 v16, v2
	v_mov_b32_e32 v17, v2
	v_mov_b32_e32 v18, v2
	v_mov_b32_e32 v19, v2
	s_waitcnt lgkmcnt(0)
	s_barrier
